# rmsnorm-residual passes: next row of X and Y prefetched into L2 with two dummy dword loads per iteration (waits bumped by 2)
# baseline (speedup 1.0000x reference)
; __device__ __forceinline__ void nr_pass(bf16* X, const bf16* Y, const float* SSQ, float* ssqX, const float* g, float* out  , int gw, int NGW, int lane) {
;     f32x4 gv[4];
; #pragma unroll
;     for (int j = 0; j < 4; ++j) gv[j] = *((const f32x4*)g + lane + 64 * j);
;     for (int r = gw; r < M_REAL; r += NGW) {
;         const float part = SSQ[(size_t)r * 32 + (lane & 31)];
;         const float s = rsqrtf(half_sum32(part) * (1.0f / 1024.0f) + EPS);
.Lnr_go_p4l0:
	v_mbcnt_lo_u32_b32 v252, -1, 0
	v_mbcnt_hi_u32_b32 v252, -1, v252
	v_mul_u32_u24_e32 v252, 24, v252
	v_mov_b32_e32 v253, 0
	s_add_i32 s18, s1, s0
	s_cmp_ge_i32 s18, s63
	s_cbranch_scc1 .LBB0_746
	v_readlane_b32 s36, v250, 2
	v_ashrrev_i32_e32 v21, 31, v20
	v_readlane_b32 s42, v250, 8
	v_readlane_b32 s43, v250, 9
	v_mbcnt_lo_u32_b32 v18, -1, 0
	v_mbcnt_hi_u32_b32 v18, -1, v18
	v_lshl_add_u64 v[16:17], v[20:21], 4, s[42:43]
	global_load_dwordx4 v[0:3], v[16:17], off
	global_load_dwordx4 v[4:7], v[16:17], off offset:1024
	global_load_dwordx4 v[8:11], v[16:17], off offset:2048
	global_load_dwordx4 v[12:15], v[16:17], off offset:3072
	v_and_b32_e32 v19, 64, v18
	s_lshl_b32 s6, s6, 3
	s_ashr_i32 s7, s0, 31
	s_ashr_i32 s8, s1, 31
	v_xor_b32_e32 v22, 1, v18
	v_add_u32_e32 v19, 64, v19
	s_add_u32 s22, s0, s1
	v_xor_b32_e32 v23, 2, v18
	v_cmp_lt_i32_e64 s[0:1], v22, v19
	v_xor_b32_e32 v25, 4, v18
	v_xor_b32_e32 v26, 8, v18
	v_cndmask_b32_e64 v22, v18, v22, s[0:1]
	v_cmp_lt_i32_e64 s[0:1], v23, v19
	v_xor_b32_e32 v27, 16, v18
	v_xor_b32_e32 v28, 32, v18
	v_cndmask_b32_e64 v23, v18, v23, s[0:1]
	v_cmp_lt_i32_e64 s[0:1], v25, v19
	s_addc_u32 s23, s7, s8
	s_lshl_b64 s[8:9], s[22:23], 2
	v_cndmask_b32_e64 v29, v18, v25, s[0:1]
	v_cmp_lt_i32_e64 s[0:1], v26, v19
	v_and_b32_e32 v16, 31, v20
	v_mov_b32_e32 v17, 0
	v_cndmask_b32_e64 v30, v18, v26, s[0:1]
	v_cmp_lt_i32_e64 s[0:1], v27, v19
	v_lshlrev_b32_e32 v16, 2, v16
	s_mov_b64 s[16:17], 0x3700000
	v_cndmask_b32_e64 v31, v18, v27, s[0:1]
	v_cmp_lt_i32_e64 s[0:1], v28, v19
	v_cmp_eq_u32_e32 vcc, 0, v20
	v_mov_b32_e32 v24, 0x358637bd
	v_cndmask_b32_e64 v18, v18, v28, s[0:1]
	s_add_u32 s0, s14, s8
	s_addc_u32 s1, s15, s9
	s_add_u32 s8, s0, 0x3f80000
	s_addc_u32 s9, s1, 0
	s_ashr_i32 s7, s6, 31
	s_lshl_b64 s[0:1], s[22:23], 7
	s_lshl_b64 s[10:11], s[6:7], 2
	s_add_u32 s0, s14, s0
	s_addc_u32 s1, s15, s1
	s_lshl_b64 s[12:13], s[6:7], 7
	s_add_u32 s14, s14, 0x4000400
	v_lshlrev_b32_e32 v28, 2, v30
	v_lshlrev_b32_e32 v30, 2, v18
	v_lshl_add_u64 v[18:19], s[0:1], 0, v[16:17]
	s_addc_u32 s15, s15, 0
	s_lshl_b64 s[0:1], s[22:23], 11
	s_mov_b32 s19, 0x800000
	s_movk_i32 s20, 0x7fff
	v_lshlrev_b32_e32 v25, 2, v22
	v_lshlrev_b32_e32 v26, 2, v23
	v_lshlrev_b32_e32 v27, 2, v29
	v_lshlrev_b32_e32 v29, 2, v31
	v_lshl_add_u64 v[18:19], v[18:19], 0, s[16:17]
	s_lshl_b64 s[16:17], s[6:7], 11
	v_lshl_add_u64 v[20:21], v[20:21], 3, s[0:1]
	v_mov_b32_e32 v16, 1
	v_readlane_b32 s37, v250, 3
	v_readlane_b32 s38, v250, 4
	v_readlane_b32 s39, v250, 5
	v_readlane_b32 s40, v250, 6
	v_readlane_b32 s41, v250, 7
	v_readlane_b32 s44, v250, 10
	v_readlane_b32 s45, v250, 11
	v_readlane_b32 s46, v250, 12
	v_readlane_b32 s47, v250, 13
	v_readlane_b32 s48, v250, 14
	v_readlane_b32 s49, v250, 15
	v_readlane_b32 s50, v250, 16
	v_readlane_b32 s51, v250, 17
	s_waitcnt vmcnt(0)
	v_mov_b32_e32 v22, v1
	v_mov_b32_e32 v23, v3
	v_mov_b32_e32 v1, v2
	v_mov_b32_e32 v2, v5
	v_mov_b32_e32 v3, v7
	v_mov_b32_e32 v5, v6
	v_mov_b32_e32 v6, v9
	v_mov_b32_e32 v7, v11
	v_mov_b32_e32 v9, v10
	v_mov_b32_e32 v10, v13
	v_mov_b32_e32 v11, v15
	v_mov_b32_e32 v13, v14
	s_branch .LBB0_744

; __device__ __forceinline__ void nr_pass(bf16* X, const bf16* Y, const float* SSQ, float* ssqX, const float* g, float* out  , int gw, int NGW, int lane) {
;     ...
;     for (int r = gw; r < M_REAL; r += NGW) {
;         const float part = SSQ[(size_t)r * 32 + (lane & 31)];
;         const float s = rsqrtf(half_sum32(part) * (1.0f / 1024.0f) + EPS);
;         v2u* x8 = (v2u*)(X + (size_t)r * 1024) + lane; const v2u* y8 = (const v2u*)(Y + (size_t)r * 1024) + lane;
;         f32x4 v[4]; float s2 = 0.f;
; #pragma unroll
;         for (int j = 0; j < 4; ++j) { const v2u xv = x8[64 * j], yv = __builtin_nontemporal_load(&y8[64 * j]);
;             v[j].x = bflo(xv.x) + bflo(yv.x) * s * gv[j].x; v[j].y = bfhi(xv.x) + bfhi(yv.x) * s * gv[j].y;
;             v[j].z = bflo(xv.y) + bflo(yv.y) * s * gv[j].z; v[j].w = bfhi(xv.y) + bfhi(yv.y) * s * gv[j].w;
;             s2 += (v[j].x * v[j].x + v[j].y * v[j].y) + (v[j].z * v[j].z + v[j].w * v[j].w); }
.LBB0_744:
	global_load_dword v31, v[18:19], off
	v_lshl_add_u64 v[14:15], s[14:15], 0, v[20:21]
	v_lshl_add_u64 v[34:35], s[2:3], 0, v[20:21]
	s_waitcnt lgkmcnt(0)
	global_load_dwordx2 v[32:33], v[14:15], off offset:-1024
	global_load_dwordx2 v[36:37], v[34:35], off nt
	global_load_dwordx2 v[38:39], v[14:15], off offset:-512
	global_load_dwordx2 v[40:41], v[34:35], off offset:512 nt
	global_load_dwordx2 v[42:43], v[14:15], off
	global_load_dwordx2 v[44:45], v[34:35], off offset:1024 nt
	global_load_dwordx2 v[46:47], v[14:15], off offset:512
	global_load_dwordx2 v[48:49], v[34:35], off offset:1536 nt
	v_lshl_add_u64 v[254:255], v[14:15], 0, s[16:17]
	v_lshl_add_u64 v[254:255], v[254:255], 0, v[252:253]
	global_load_dword v251, v[254:255], off offset:-1024
	v_lshl_add_u64 v[254:255], v[34:35], 0, s[16:17]
	v_lshl_add_u64 v[254:255], v[254:255], 0, v[252:253]
	global_load_dword v251, v[254:255], off
	s_waitcnt vmcnt(8)
	v_lshlrev_b32_e32 v51, 16, v37
	v_lshlrev_b32_e32 v50, 16, v36
	ds_bpermute_b32 v56, v25, v31
	v_and_b32_e32 v37, 0xffff0000, v37
	v_and_b32_e32 v36, 0xffff0000, v36
	s_waitcnt vmcnt(6)
	v_lshlrev_b32_e32 v55, 16, v41
	v_lshlrev_b32_e32 v54, 16, v40
	s_waitcnt lgkmcnt(0)
	v_add_f32_e32 v31, v31, v56
	ds_bpermute_b32 v56, v26, v31
	v_and_b32_e32 v41, 0xffff0000, v41
	v_and_b32_e32 v40, 0xffff0000, v40
	v_lshlrev_b32_e32 v35, 16, v33
	v_lshlrev_b32_e32 v34, 16, v32
	s_waitcnt lgkmcnt(0)
	v_add_f32_e32 v31, v31, v56
	ds_bpermute_b32 v60, v27, v31
	v_and_b32_e32 v33, 0xffff0000, v33
	v_and_b32_e32 v32, 0xffff0000, v32
	v_lshlrev_b32_e32 v53, 16, v39
	v_lshlrev_b32_e32 v52, 16, v38
	s_waitcnt lgkmcnt(0)
	v_add_f32_e32 v31, v31, v60
	ds_bpermute_b32 v60, v28, v31
	v_and_b32_e32 v39, 0xffff0000, v39
	v_and_b32_e32 v38, 0xffff0000, v38
	s_waitcnt vmcnt(4)
	v_lshlrev_b32_e32 v59, 16, v45
	v_lshlrev_b32_e32 v58, 16, v44
	s_waitcnt lgkmcnt(0)
	v_add_f32_e32 v31, v31, v60
	ds_bpermute_b32 v64, v29, v31
	v_and_b32_e32 v45, 0xffff0000, v45
	v_and_b32_e32 v44, 0xffff0000, v44
	s_waitcnt vmcnt(2)
	v_lshlrev_b32_e32 v63, 16, v49
	v_lshlrev_b32_e32 v62, 16, v48
	s_waitcnt lgkmcnt(0)
	v_add_f32_e32 v31, v31, v64
	v_fmamk_f32 v31, v31, 0x3a800000, v24
	v_mul_f32_e32 v64, 0x4b800000, v31
	v_cmp_gt_f32_e64 s[0:1], s19, v31
	v_and_b32_e32 v49, 0xffff0000, v49
	v_and_b32_e32 v48, 0xffff0000, v48
	v_cndmask_b32_e64 v31, v31, v64, s[0:1]
	v_rsq_f32_e32 v31, v31
	v_lshlrev_b32_e32 v57, 16, v43
	v_lshlrev_b32_e32 v56, 16, v42
	v_and_b32_e32 v43, 0xffff0000, v43
	v_mul_f32_e32 v64, 0x45800000, v31
	v_cndmask_b32_e64 v64, v31, v64, s[0:1]
	v_pk_mul_f32 v[36:37], v[64:65], v[36:37] op_sel_hi:[0,1]
	v_pk_mul_f32 v[40:41], v[64:65], v[40:41] op_sel_hi:[0,1]
	v_and_b32_e32 v42, 0xffff0000, v42
	v_lshlrev_b32_e32 v61, 16, v47
	v_lshlrev_b32_e32 v60, 16, v46
	v_and_b32_e32 v47, 0xffff0000, v47
	v_and_b32_e32 v46, 0xffff0000, v46
	v_pk_mul_f32 v[50:51], v[64:65], v[50:51] op_sel_hi:[0,1]
	v_pk_mul_f32 v[54:55], v[64:65], v[54:55] op_sel_hi:[0,1]
	v_pk_mul_f32 v[58:59], v[64:65], v[58:59] op_sel_hi:[0,1]
	v_pk_mul_f32 v[44:45], v[64:65], v[44:45] op_sel_hi:[0,1]
	v_pk_mul_f32 v[48:49], v[64:65], v[48:49] op_sel_hi:[0,1]
	v_pk_fma_f32 v[32:33], v[22:23], v[36:37], v[32:33]
	v_pk_fma_f32 v[38:39], v[2:3], v[40:41], v[38:39]
	v_pk_fma_f32 v[34:35], v[0:1], v[50:51], v[34:35]
	v_pk_fma_f32 v[36:37], v[4:5], v[54:55], v[52:53]
	v_pk_fma_f32 v[40:41], v[8:9], v[58:59], v[56:57]
	v_pk_fma_f32 v[42:43], v[6:7], v[44:45], v[42:43]
	v_pk_fma_f32 v[46:47], v[10:11], v[48:49], v[46:47]
	v_pk_mul_f32 v[48:49], v[32:33], v[32:33]
	v_and_b32_sdwa v57, v33, v16 dst_sel:DWORD dst_unused:UNUSED_PAD src0_sel:WORD_1 src1_sel:DWORD
	v_and_b32_sdwa v58, v32, v16 dst_sel:DWORD dst_unused:UNUSED_PAD src0_sel:WORD_1 src1_sel:DWORD
	v_pk_mul_f32 v[50:51], v[38:39], v[38:39]
	v_pk_mul_f32 v[62:63], v[64:65], v[62:63] op_sel_hi:[0,1]
	v_and_b32_sdwa v31, v35, v16 dst_sel:DWORD dst_unused:UNUSED_PAD src0_sel:WORD_1 src1_sel:DWORD
	v_and_b32_sdwa v56, v34, v16 dst_sel:DWORD dst_unused:UNUSED_PAD src0_sel:WORD_1 src1_sel:DWORD
	v_pk_mul_f32 v[52:53], v[42:43], v[42:43]
	v_pk_fma_f32 v[48:49], v[34:35], v[34:35], v[48:49]
	v_add3_u32 v57, v33, v57, s20
	v_add3_u32 v58, v32, v58, s20
	v_pk_fma_f32 v[32:33], v[36:37], v[36:37], v[50:51]
	v_pk_fma_f32 v[44:45], v[12:13], v[62:63], v[60:61]
	v_and_b32_sdwa v59, v37, v16 dst_sel:DWORD dst_unused:UNUSED_PAD src0_sel:WORD_1 src1_sel:DWORD
	v_and_b32_sdwa v60, v36, v16 dst_sel:DWORD dst_unused:UNUSED_PAD src0_sel:WORD_1 src1_sel:DWORD
	v_pk_mul_f32 v[54:55], v[46:47], v[46:47]
	v_add3_u32 v56, v34, v56, s20
	v_add3_u32 v31, v35, v31, s20
	v_pk_fma_f32 v[34:35], v[40:41], v[40:41], v[52:53]
	v_add_f32_e32 v32, v32, v33
	v_add_f32_e32 v33, v48, v49
	v_add3_u32 v50, v36, v60, s20
	v_add3_u32 v51, v37, v59, s20
	v_pk_fma_f32 v[36:37], v[44:45], v[44:45], v[54:55]
	v_add_f32_e32 v34, v34, v35
	v_add_f32_e32 v32, v33, v32
	v_add_f32_e32 v35, v36, v37
	v_add_f32_e32 v32, v34, v32
	v_add_f32_e32 v32, v32, v35
	ds_bpermute_b32 v33, v25, v32
	v_and_b32_sdwa v61, v39, v16 dst_sel:DWORD dst_unused:UNUSED_PAD src0_sel:WORD_1 src1_sel:DWORD
	v_add3_u32 v39, v39, v61, s20
	v_and_b32_e32 v37, 0xffff0000, v39
	v_and_b32_e32 v35, 0xffff0000, v57
	s_waitcnt lgkmcnt(0)
; __device__ __forceinline__ unsigned f2bf(float f) { unsigned u = __builtin_bit_cast(unsigned, f); return (u + 0x7fffu + ((u >> 16) & 1u)) >> 16; }
; __device__ __forceinline__ unsigned pk2(float lo, float hi) { return f2bf(lo) | (f2bf(hi) << 16); }
; __device__ __forceinline__ void nr_pass(bf16* X, const bf16* Y, const float* SSQ, float* ssqX, const float* g, float* out  , int gw, int NGW, int lane) {
;     ...
;             s2 = wave_sum(s2);
; #pragma unroll
;             for (int j = 0; j < 4; ++j) x8[64 * j] = (v2u){pk2(v[j].x, v[j].y), pk2(v[j].z, v[j].w)};
;             if (lane == 0) ssqX[r] = s2;
	v_add_f32_e32 v32, v32, v33
	ds_bpermute_b32 v33, v26, v32
	v_and_b32_sdwa v62, v38, v16 dst_sel:DWORD dst_unused:UNUSED_PAD src0_sel:WORD_1 src1_sel:DWORD
	v_and_b32_sdwa v66, v42, v16 dst_sel:DWORD dst_unused:UNUSED_PAD src0_sel:WORD_1 src1_sel:DWORD
	v_add3_u32 v38, v38, v62, s20
	v_and_b32_sdwa v67, v45, v16 dst_sel:DWORD dst_unused:UNUSED_PAD src0_sel:WORD_1 src1_sel:DWORD
	s_waitcnt lgkmcnt(0)
	v_add_f32_e32 v32, v32, v33
	ds_bpermute_b32 v39, v27, v32
	v_or_b32_sdwa v33, v35, v31 dst_sel:DWORD dst_unused:UNUSED_PAD src0_sel:DWORD src1_sel:WORD_1
	v_and_b32_sdwa v68, v44, v16 dst_sel:DWORD dst_unused:UNUSED_PAD src0_sel:WORD_1 src1_sel:DWORD
	v_and_b32_sdwa v69, v47, v16 dst_sel:DWORD dst_unused:UNUSED_PAD src0_sel:WORD_1 src1_sel:DWORD
	v_add3_u32 v34, v42, v66, s20
	s_waitcnt lgkmcnt(0)
	v_add_f32_e32 v31, v32, v39
	ds_bpermute_b32 v39, v28, v31
	v_and_b32_e32 v38, 0xffff0000, v38
	v_add3_u32 v42, v44, v68, s20
	v_add3_u32 v44, v45, v67, s20
	v_add3_u32 v45, v47, v69, s20
	s_waitcnt lgkmcnt(0)
	v_add_f32_e32 v31, v31, v39
	v_and_b32_e32 v47, 0xffff0000, v34
	v_or_b32_sdwa v34, v38, v50 dst_sel:DWORD dst_unused:UNUSED_PAD src0_sel:DWORD src1_sel:WORD_1
	ds_bpermute_b32 v38, v29, v31
	v_and_b32_sdwa v65, v43, v16 dst_sel:DWORD dst_unused:UNUSED_PAD src0_sel:WORD_1 src1_sel:DWORD
	v_and_b32_sdwa v63, v41, v16 dst_sel:DWORD dst_unused:UNUSED_PAD src0_sel:WORD_1 src1_sel:DWORD
	v_and_b32_sdwa v64, v40, v16 dst_sel:DWORD dst_unused:UNUSED_PAD src0_sel:WORD_1 src1_sel:DWORD
	v_add3_u32 v43, v43, v65, s20
	v_and_b32_e32 v36, 0xffff0000, v58
	v_add3_u32 v40, v40, v64, s20
	v_add3_u32 v41, v41, v63, s20
	v_and_b32_e32 v43, 0xffff0000, v43
	v_or_b32_sdwa v32, v36, v56 dst_sel:DWORD dst_unused:UNUSED_PAD src0_sel:DWORD src1_sel:WORD_1
	s_waitcnt lgkmcnt(0)
	v_add_f32_e32 v31, v31, v38
	v_or_b32_sdwa v35, v37, v51 dst_sel:DWORD dst_unused:UNUSED_PAD src0_sel:DWORD src1_sel:WORD_1
	v_or_b32_sdwa v37, v43, v41 dst_sel:DWORD dst_unused:UNUSED_PAD src0_sel:DWORD src1_sel:WORD_1
	v_or_b32_sdwa v36, v47, v40 dst_sel:DWORD dst_unused:UNUSED_PAD src0_sel:DWORD src1_sel:WORD_1
	global_store_dwordx2 v[14:15], v[32:33], off offset:-1024
	global_store_dwordx2 v[14:15], v[34:35], off offset:-512
	global_store_dwordx2 v[14:15], v[36:37], off
	ds_bpermute_b32 v32, v30, v31
	v_and_b32_sdwa v70, v46, v16 dst_sel:DWORD dst_unused:UNUSED_PAD src0_sel:WORD_1 src1_sel:DWORD
	v_add3_u32 v46, v46, v70, s20
	v_and_b32_e32 v33, 0xffff0000, v45
	v_and_b32_e32 v34, 0xffff0000, v46
	v_or_b32_sdwa v35, v33, v44 dst_sel:DWORD dst_unused:UNUSED_PAD src0_sel:DWORD src1_sel:WORD_1
	v_or_b32_sdwa v34, v34, v42 dst_sel:DWORD dst_unused:UNUSED_PAD src0_sel:DWORD src1_sel:WORD_1
	global_store_dwordx2 v[14:15], v[34:35], off offset:512
	s_and_saveexec_b64 s[0:1], vcc
	s_cbranch_execz .LBB0_743
	s_waitcnt lgkmcnt(0)
	v_add_f32_e32 v14, v31, v32
	global_store_dword v17, v14, s[8:9]
	s_branch .LBB0_743

; __device__ __forceinline__ void nr_pass(bf16* X, const bf16* Y, const float* SSQ, float* ssqX, const float* g, float* out  , int gw, int NGW, int lane) {
;     f32x4 gv[4];
; #pragma unroll
;     for (int j = 0; j < 4; ++j) gv[j] = *((const f32x4*)g + lane + 64 * j);
;     for (int r = gw; r < M_REAL; r += NGW) {
;         const float part = SSQ[(size_t)r * 32 + (lane & 31)];
;         const float s = rsqrtf(half_sum32(part) * (1.0f / 1024.0f) + EPS);
.Lnr_go_p7l0:
	v_mbcnt_lo_u32_b32 v252, -1, 0
	v_mbcnt_hi_u32_b32 v252, -1, v252
	v_mul_u32_u24_e32 v252, 24, v252
	v_mov_b32_e32 v253, 0
	s_add_i32 s14, s1, s0
	s_cmp_ge_i32 s14, s63
	s_cbranch_scc1 .LBB0_958
	v_ashrrev_i32_e32 v17, 31, v16
	v_lshl_add_u64 v[18:19], v[16:17], 4, s[88:89]
	global_load_dwordx4 v[0:3], v[18:19], off
	s_waitcnt lgkmcnt(0)
	global_load_dwordx4 v[4:7], v[18:19], off offset:1024
	global_load_dwordx4 v[8:11], v[18:19], off offset:2048
	global_load_dwordx4 v[12:15], v[18:19], off offset:3072
	v_mbcnt_lo_u32_b32 v19, -1, 0
	v_mbcnt_hi_u32_b32 v19, -1, v19
	v_and_b32_e32 v20, 64, v19
	s_lshl_b32 s6, s6, 3
	s_ashr_i32 s7, s0, 31
	s_ashr_i32 s9, s1, 31
	v_xor_b32_e32 v21, 1, v19
	v_add_u32_e32 v20, 64, v20
	s_add_u32 s8, s0, s1
	v_xor_b32_e32 v24, 2, v19
	v_cmp_lt_i32_e64 s[0:1], v21, v20
	v_xor_b32_e32 v25, 4, v19
	v_xor_b32_e32 v26, 8, v19
	v_cndmask_b32_e64 v21, v19, v21, s[0:1]
	v_cmp_lt_i32_e64 s[0:1], v24, v20
	v_xor_b32_e32 v27, 16, v19
	s_addc_u32 s9, s7, s9
	v_cndmask_b32_e64 v29, v19, v24, s[0:1]
	v_cmp_lt_i32_e64 s[0:1], v25, v20
	v_xor_b32_e32 v28, 32, v19
	s_lshl_b64 s[10:11], s[8:9], 2
	v_cndmask_b32_e64 v30, v19, v25, s[0:1]
	v_cmp_lt_i32_e64 s[0:1], v26, v20
	s_add_u32 s19, s10, 0x3f80000
	v_and_b32_e32 v18, 31, v16
	v_cndmask_b32_e64 v31, v19, v26, s[0:1]
	v_cmp_lt_i32_e64 s[0:1], v27, v20
	s_addc_u32 s20, s11, 0
	s_lshl_b64 s[12:13], s[8:9], 7
	v_cndmask_b32_e64 v32, v19, v27, s[0:1]
	v_cmp_lt_i32_e64 s[0:1], v28, v20
	s_mov_b64 s[22:23], 0x3700000
	v_lshlrev_b32_e32 v25, 2, v29
	v_cndmask_b32_e64 v19, v19, v28, s[0:1]
	v_lshlrev_b32_e32 v29, 2, v19
	s_ashr_i32 s7, s6, 31
	s_lshl_b64 s[0:1], s[8:9], 11
	v_lshl_or_b32 v18, v18, 2, s12
	v_mov_b32_e32 v19, s13
	v_cmp_eq_u32_e32 vcc, 0, v16
	v_mov_b32_e32 v22, 0x358637bd
	s_mov_b32 s15, 0x800000
	s_brev_b32 s16, 32
	s_mov_b32 s17, 0xc100000
	s_movk_i32 s18, 0x7fff
	v_mov_b32_e32 v23, 0
	v_lshlrev_b32_e32 v24, 2, v21
	v_lshlrev_b32_e32 v26, 2, v30
	v_lshlrev_b32_e32 v27, 2, v31
	v_lshlrev_b32_e32 v28, 2, v32
	s_lshl_b64 s[8:9], s[6:7], 2
	v_lshl_add_u64 v[16:17], v[16:17], 3, s[0:1]
	s_lshl_b64 s[10:11], s[6:7], 11
	s_lshl_b64 s[12:13], s[6:7], 7
	v_lshl_add_u64 v[18:19], v[18:19], 0, s[22:23]
	v_mov_b32_e32 v30, 1
	s_waitcnt vmcnt(0)
	v_mov_b32_e32 v20, v1
	v_mov_b32_e32 v21, v3
	v_mov_b32_e32 v1, v2
	v_mov_b32_e32 v2, v5
	v_mov_b32_e32 v3, v7
	v_mov_b32_e32 v5, v6
	v_mov_b32_e32 v6, v9
	v_mov_b32_e32 v7, v11
	v_mov_b32_e32 v9, v10
	v_mov_b32_e32 v10, v13
	v_mov_b32_e32 v11, v15
	v_mov_b32_e32 v13, v14
	s_branch .LBB0_956

; __device__ __forceinline__ void nr_pass(bf16* X, const bf16* Y, const float* SSQ, float* ssqX, const float* g, float* out  , int gw, int NGW, int lane) {
;     ...
;     for (int r = gw; r < M_REAL; r += NGW) {
;         const float part = SSQ[(size_t)r * 32 + (lane & 31)];
;         const float s = rsqrtf(half_sum32(part) * (1.0f / 1024.0f) + EPS);
;         v2u* x8 = (v2u*)(X + (size_t)r * 1024) + lane; const v2u* y8 = (const v2u*)(Y + (size_t)r * 1024) + lane;
;         f32x4 v[4]; float s2 = 0.f;
; #pragma unroll
;         for (int j = 0; j < 4; ++j) { const v2u xv = x8[64 * j], yv = __builtin_nontemporal_load(&y8[64 * j]);
;             v[j].x = bflo(xv.x) + bflo(yv.x) * s * gv[j].x; v[j].y = bfhi(xv.x) + bfhi(yv.x) * s * gv[j].y;
;             v[j].z = bflo(xv.y) + bflo(yv.y) * s * gv[j].z; v[j].w = bfhi(xv.y) + bfhi(yv.y) * s * gv[j].w;
;             s2 += (v[j].x * v[j].x + v[j].y * v[j].y) + (v[j].z * v[j].z + v[j].w * v[j].w); }
.LBB0_956:
	v_lshl_add_u64 v[34:35], s[4:5], 0, v[16:17]
	s_waitcnt lgkmcnt(0)
	v_lshl_add_u64 v[32:33], s[4:5], 0, v[18:19]
	v_add_co_u32_e64 v14, s[0:1], s16, v34
	s_nop 1
	v_addc_co_u32_e64 v15, s[0:1], 0, v35, s[0:1]
	global_load_dword v31, v[32:33], off
	global_load_dwordx2 v[36:37], v[14:15], off
	v_add_co_u32_e64 v32, s[0:1], s17, v34
	s_waitcnt vmcnt(1)
	ds_bpermute_b32 v56, v24, v31
	v_addc_co_u32_e64 v33, s[0:1], 0, v35, s[0:1]
	global_load_dwordx2 v[34:35], v[32:33], off nt
	global_load_dwordx2 v[38:39], v[14:15], off offset:512
	global_load_dwordx2 v[40:41], v[32:33], off offset:512 nt
	global_load_dwordx2 v[42:43], v[14:15], off offset:1024
	global_load_dwordx2 v[44:45], v[32:33], off offset:1024 nt
	global_load_dwordx2 v[46:47], v[14:15], off offset:1536
	global_load_dwordx2 v[48:49], v[32:33], off offset:1536 nt
	v_lshl_add_u64 v[254:255], v[14:15], 0, s[10:11]
	v_lshl_add_u64 v[254:255], v[254:255], 0, v[252:253]
	global_load_dword v251, v[254:255], off
	v_lshl_add_u64 v[254:255], v[32:33], 0, s[10:11]
	v_lshl_add_u64 v[254:255], v[254:255], 0, v[252:253]
	global_load_dword v251, v[254:255], off
	s_waitcnt vmcnt(9)
	v_lshlrev_b32_e32 v33, 16, v37
	s_waitcnt lgkmcnt(0)
	v_add_f32_e32 v31, v31, v56
	ds_bpermute_b32 v56, v25, v31
	v_lshlrev_b32_e32 v32, 16, v36
	v_and_b32_e32 v37, 0xffff0000, v37
	v_and_b32_e32 v36, 0xffff0000, v36
	s_waitcnt lgkmcnt(0)
	v_add_f32_e32 v31, v31, v56
	ds_bpermute_b32 v60, v26, v31
	s_waitcnt lgkmcnt(0)
	v_add_f32_e32 v31, v31, v60
	ds_bpermute_b32 v60, v27, v31
	s_waitcnt lgkmcnt(0)
	v_add_f32_e32 v31, v31, v60
	ds_bpermute_b32 v64, v28, v31
	s_waitcnt lgkmcnt(0)
	v_add_f32_e32 v31, v31, v64
	v_fmamk_f32 v31, v31, 0x3a800000, v22
	v_mul_f32_e32 v64, 0x4b800000, v31
	v_cmp_gt_f32_e64 s[0:1], s15, v31
	s_waitcnt vmcnt(8)
	v_lshlrev_b32_e32 v51, 16, v35
	v_cndmask_b32_e64 v31, v31, v64, s[0:1]
	v_rsq_f32_e32 v31, v31
	v_lshlrev_b32_e32 v50, 16, v34
	v_and_b32_e32 v35, 0xffff0000, v35
	v_and_b32_e32 v34, 0xffff0000, v34
	v_mul_f32_e32 v64, 0x45800000, v31
	s_waitcnt vmcnt(6)
	v_lshlrev_b32_e32 v55, 16, v41
	v_lshlrev_b32_e32 v54, 16, v40
	v_and_b32_e32 v41, 0xffff0000, v41
	v_and_b32_e32 v40, 0xffff0000, v40
	v_cndmask_b32_e64 v64, v31, v64, s[0:1]
	v_lshlrev_b32_e32 v53, 16, v39
	v_lshlrev_b32_e32 v52, 16, v38
	v_and_b32_e32 v39, 0xffff0000, v39
	v_and_b32_e32 v38, 0xffff0000, v38
	s_waitcnt vmcnt(4)
	v_lshlrev_b32_e32 v59, 16, v45
	v_lshlrev_b32_e32 v58, 16, v44
	v_and_b32_e32 v45, 0xffff0000, v45
	v_and_b32_e32 v44, 0xffff0000, v44
	s_waitcnt vmcnt(2)
	v_lshlrev_b32_e32 v63, 16, v49
	v_lshlrev_b32_e32 v62, 16, v48
	v_and_b32_e32 v49, 0xffff0000, v49
	v_and_b32_e32 v48, 0xffff0000, v48
	v_pk_mul_f32 v[50:51], v[64:65], v[50:51] op_sel_hi:[0,1]
	v_pk_mul_f32 v[34:35], v[64:65], v[34:35] op_sel_hi:[0,1]
	v_pk_mul_f32 v[40:41], v[64:65], v[40:41] op_sel_hi:[0,1]
	v_lshlrev_b32_e32 v57, 16, v43
	v_lshlrev_b32_e32 v56, 16, v42
	v_and_b32_e32 v43, 0xffff0000, v43
	v_and_b32_e32 v42, 0xffff0000, v42
	v_lshlrev_b32_e32 v61, 16, v47
	v_lshlrev_b32_e32 v60, 16, v46
	v_and_b32_e32 v47, 0xffff0000, v47
	v_and_b32_e32 v46, 0xffff0000, v46
	v_pk_mul_f32 v[54:55], v[64:65], v[54:55] op_sel_hi:[0,1]
	v_pk_mul_f32 v[58:59], v[64:65], v[58:59] op_sel_hi:[0,1]
	v_pk_mul_f32 v[44:45], v[64:65], v[44:45] op_sel_hi:[0,1]
	v_pk_mul_f32 v[48:49], v[64:65], v[48:49] op_sel_hi:[0,1]
	v_pk_fma_f32 v[32:33], v[0:1], v[50:51], v[32:33]
	v_pk_fma_f32 v[34:35], v[20:21], v[34:35], v[36:37]
	v_pk_fma_f32 v[38:39], v[2:3], v[40:41], v[38:39]
	v_pk_fma_f32 v[36:37], v[4:5], v[54:55], v[52:53]
	v_pk_fma_f32 v[40:41], v[8:9], v[58:59], v[56:57]
	v_pk_fma_f32 v[42:43], v[6:7], v[44:45], v[42:43]
	v_pk_fma_f32 v[46:47], v[10:11], v[48:49], v[46:47]
	v_pk_mul_f32 v[48:49], v[34:35], v[34:35]
	v_and_b32_sdwa v31, v33, v30 dst_sel:DWORD dst_unused:UNUSED_PAD src0_sel:WORD_1 src1_sel:DWORD
	v_and_b32_sdwa v56, v32, v30 dst_sel:DWORD dst_unused:UNUSED_PAD src0_sel:WORD_1 src1_sel:DWORD
	v_pk_mul_f32 v[50:51], v[38:39], v[38:39]
	v_pk_mul_f32 v[62:63], v[64:65], v[62:63] op_sel_hi:[0,1]
	v_and_b32_sdwa v57, v35, v30 dst_sel:DWORD dst_unused:UNUSED_PAD src0_sel:WORD_1 src1_sel:DWORD
	v_and_b32_sdwa v58, v34, v30 dst_sel:DWORD dst_unused:UNUSED_PAD src0_sel:WORD_1 src1_sel:DWORD
	v_pk_mul_f32 v[52:53], v[42:43], v[42:43]
	v_pk_fma_f32 v[48:49], v[32:33], v[32:33], v[48:49]
	v_add3_u32 v56, v32, v56, s18
	v_add3_u32 v31, v33, v31, s18
	v_pk_fma_f32 v[32:33], v[36:37], v[36:37], v[50:51]
	v_pk_fma_f32 v[44:45], v[12:13], v[62:63], v[60:61]
	v_and_b32_sdwa v59, v37, v30 dst_sel:DWORD dst_unused:UNUSED_PAD src0_sel:WORD_1 src1_sel:DWORD
	v_and_b32_sdwa v60, v36, v30 dst_sel:DWORD dst_unused:UNUSED_PAD src0_sel:WORD_1 src1_sel:DWORD
	v_pk_mul_f32 v[54:55], v[46:47], v[46:47]
	v_add3_u32 v57, v35, v57, s18
	v_add3_u32 v58, v34, v58, s18
	v_pk_fma_f32 v[34:35], v[40:41], v[40:41], v[52:53]
	v_add_f32_e32 v32, v32, v33
	v_add_f32_e32 v33, v48, v49
	v_add3_u32 v50, v36, v60, s18
	v_add3_u32 v51, v37, v59, s18
	v_pk_fma_f32 v[36:37], v[44:45], v[44:45], v[54:55]
	v_add_f32_e32 v34, v34, v35
	v_add_f32_e32 v32, v33, v32
	v_add_f32_e32 v35, v36, v37
	v_add_f32_e32 v32, v34, v32
	v_add_f32_e32 v32, v32, v35
	ds_bpermute_b32 v33, v24, v32
	v_and_b32_sdwa v61, v39, v30 dst_sel:DWORD dst_unused:UNUSED_PAD src0_sel:WORD_1 src1_sel:DWORD
	v_add3_u32 v39, v39, v61, s18
	v_and_b32_e32 v37, 0xffff0000, v39
	v_and_b32_e32 v35, 0xffff0000, v57
	s_waitcnt lgkmcnt(0)
; __device__ __forceinline__ unsigned pk2(float lo, float hi) { return f2bf(lo) | (f2bf(hi) << 16); }
; __device__ __forceinline__ void nr_pass(bf16* X, const bf16* Y, const float* SSQ, float* ssqX, const float* g, float* out  , int gw, int NGW, int lane) {
;     ...
;             s2 = wave_sum(s2);
; #pragma unroll
;             for (int j = 0; j < 4; ++j) x8[64 * j] = (v2u){pk2(v[j].x, v[j].y), pk2(v[j].z, v[j].w)};
;             if (lane == 0) ssqX[r] = s2;
	v_add_f32_e32 v32, v32, v33
	ds_bpermute_b32 v33, v25, v32
	v_and_b32_sdwa v62, v38, v30 dst_sel:DWORD dst_unused:UNUSED_PAD src0_sel:WORD_1 src1_sel:DWORD
	v_and_b32_sdwa v66, v42, v30 dst_sel:DWORD dst_unused:UNUSED_PAD src0_sel:WORD_1 src1_sel:DWORD
	v_add3_u32 v38, v38, v62, s18
	v_and_b32_sdwa v67, v45, v30 dst_sel:DWORD dst_unused:UNUSED_PAD src0_sel:WORD_1 src1_sel:DWORD
	s_waitcnt lgkmcnt(0)
	v_add_f32_e32 v32, v32, v33
	ds_bpermute_b32 v39, v26, v32
	v_or_b32_sdwa v33, v35, v31 dst_sel:DWORD dst_unused:UNUSED_PAD src0_sel:DWORD src1_sel:WORD_1
	v_and_b32_sdwa v68, v44, v30 dst_sel:DWORD dst_unused:UNUSED_PAD src0_sel:WORD_1 src1_sel:DWORD
	v_and_b32_sdwa v69, v47, v30 dst_sel:DWORD dst_unused:UNUSED_PAD src0_sel:WORD_1 src1_sel:DWORD
	v_add3_u32 v34, v42, v66, s18
	s_waitcnt lgkmcnt(0)
	v_add_f32_e32 v31, v32, v39
	ds_bpermute_b32 v39, v27, v31
	v_and_b32_e32 v38, 0xffff0000, v38
	v_add3_u32 v42, v44, v68, s18
	v_add3_u32 v44, v45, v67, s18
	v_add3_u32 v45, v47, v69, s18
	s_waitcnt lgkmcnt(0)
	v_add_f32_e32 v31, v31, v39
	v_and_b32_e32 v47, 0xffff0000, v34
	v_or_b32_sdwa v34, v38, v50 dst_sel:DWORD dst_unused:UNUSED_PAD src0_sel:DWORD src1_sel:WORD_1
	ds_bpermute_b32 v38, v28, v31
	v_and_b32_sdwa v65, v43, v30 dst_sel:DWORD dst_unused:UNUSED_PAD src0_sel:WORD_1 src1_sel:DWORD
	v_and_b32_sdwa v63, v41, v30 dst_sel:DWORD dst_unused:UNUSED_PAD src0_sel:WORD_1 src1_sel:DWORD
	v_and_b32_sdwa v64, v40, v30 dst_sel:DWORD dst_unused:UNUSED_PAD src0_sel:WORD_1 src1_sel:DWORD
	v_add3_u32 v43, v43, v65, s18
	v_and_b32_e32 v36, 0xffff0000, v58
	v_add3_u32 v40, v40, v64, s18
	v_add3_u32 v41, v41, v63, s18
	v_and_b32_e32 v43, 0xffff0000, v43
	v_or_b32_sdwa v32, v36, v56 dst_sel:DWORD dst_unused:UNUSED_PAD src0_sel:DWORD src1_sel:WORD_1
	s_waitcnt lgkmcnt(0)
	v_add_f32_e32 v31, v31, v38
	v_or_b32_sdwa v35, v37, v51 dst_sel:DWORD dst_unused:UNUSED_PAD src0_sel:DWORD src1_sel:WORD_1
	v_or_b32_sdwa v37, v43, v41 dst_sel:DWORD dst_unused:UNUSED_PAD src0_sel:DWORD src1_sel:WORD_1
	v_or_b32_sdwa v36, v47, v40 dst_sel:DWORD dst_unused:UNUSED_PAD src0_sel:DWORD src1_sel:WORD_1
	global_store_dwordx2 v[14:15], v[32:33], off
	global_store_dwordx2 v[14:15], v[34:35], off offset:512
	global_store_dwordx2 v[14:15], v[36:37], off offset:1024
	ds_bpermute_b32 v32, v29, v31
	v_and_b32_sdwa v70, v46, v30 dst_sel:DWORD dst_unused:UNUSED_PAD src0_sel:WORD_1 src1_sel:DWORD
	v_add3_u32 v46, v46, v70, s18
	v_and_b32_e32 v33, 0xffff0000, v45
	v_and_b32_e32 v34, 0xffff0000, v46
	v_or_b32_sdwa v35, v33, v44 dst_sel:DWORD dst_unused:UNUSED_PAD src0_sel:DWORD src1_sel:WORD_1
	v_or_b32_sdwa v34, v34, v42 dst_sel:DWORD dst_unused:UNUSED_PAD src0_sel:DWORD src1_sel:WORD_1
	global_store_dwordx2 v[14:15], v[34:35], off offset:1536
	s_and_saveexec_b64 s[0:1], vcc
	s_cbranch_execz .LBB0_955
	s_add_u32 s22, s4, s19
	s_waitcnt lgkmcnt(0)
	v_add_f32_e32 v14, v31, v32
	s_addc_u32 s23, s5, s20
	global_store_dword v23, v14, s[22:23]
	s_branch .LBB0_955

; __device__ __forceinline__ void nr_pass(bf16* X, const bf16* Y, const float* SSQ, float* ssqX, const float* g, float* out  , int gw, int NGW, int lane) {
;     f32x4 gv[4];
; #pragma unroll
;     for (int j = 0; j < 4; ++j) gv[j] = *((const f32x4*)g + lane + 64 * j);
;     for (int r = gw; r < M_REAL; r += NGW) {
;         const float part = SSQ[(size_t)r * 32 + (lane & 31)];
;         const float s = rsqrtf(half_sum32(part) * (1.0f / 1024.0f) + EPS);
.Lnr_go_p4l1:
	v_mbcnt_lo_u32_b32 v252, -1, 0
	v_mbcnt_hi_u32_b32 v252, -1, v252
	v_mul_u32_u24_e32 v252, 24, v252
	v_mov_b32_e32 v253, 0
	s_add_i32 s18, s1, s0
	s_cmp_ge_i32 s18, s63
	s_cbranch_scc1 .LBB0_1546
	v_readlane_b32 s36, v250, 2
	v_ashrrev_i32_e32 v21, 31, v20
	v_readlane_b32 s42, v250, 8
	v_readlane_b32 s43, v250, 9
	s_mov_b64 s[8:9], 0x1000
	v_mbcnt_lo_u32_b32 v18, -1, 0
	v_lshl_add_u64 v[12:13], v[20:21], 4, s[42:43]
	v_lshl_add_u64 v[14:15], v[12:13], 0, s[8:9]
	v_add_co_u32_e32 v12, vcc, 0x1000, v12
	global_load_dwordx4 v[0:3], v[14:15], off offset:1024
	global_load_dwordx4 v[4:7], v[14:15], off offset:2048
	global_load_dwordx4 v[8:11], v[14:15], off offset:3072
	v_addc_co_u32_e32 v13, vcc, 0, v13, vcc
	global_load_dwordx4 v[12:15], v[12:13], off
	v_mbcnt_hi_u32_b32 v18, -1, v18
	v_and_b32_e32 v19, 64, v18
	s_lshl_b32 s6, s6, 3
	s_ashr_i32 s7, s0, 31
	s_ashr_i32 s8, s1, 31
	v_xor_b32_e32 v22, 1, v18
	v_add_u32_e32 v19, 64, v19
	s_add_u32 s20, s0, s1
	v_xor_b32_e32 v23, 2, v18
	v_cmp_lt_i32_e64 s[0:1], v22, v19
	v_xor_b32_e32 v25, 4, v18
	v_xor_b32_e32 v26, 8, v18
	v_cndmask_b32_e64 v22, v18, v22, s[0:1]
	v_cmp_lt_i32_e64 s[0:1], v23, v19
	v_xor_b32_e32 v27, 16, v18
	v_xor_b32_e32 v28, 32, v18
	v_cndmask_b32_e64 v23, v18, v23, s[0:1]
	v_cmp_lt_i32_e64 s[0:1], v25, v19
	s_addc_u32 s21, s7, s8
	s_lshl_b64 s[8:9], s[20:21], 2
	v_cndmask_b32_e64 v29, v18, v25, s[0:1]
	v_cmp_lt_i32_e64 s[0:1], v26, v19
	v_and_b32_e32 v16, 31, v20
	v_mov_b32_e32 v17, 0
	v_cndmask_b32_e64 v30, v18, v26, s[0:1]
	v_cmp_lt_i32_e64 s[0:1], v27, v19
	v_lshlrev_b32_e32 v16, 2, v16
	s_mov_b64 s[16:17], 0x3700000
	v_cndmask_b32_e64 v31, v18, v27, s[0:1]
	v_cmp_lt_i32_e64 s[0:1], v28, v19
	v_cmp_eq_u32_e32 vcc, 0, v20
	v_mov_b32_e32 v24, 0x358637bd
	v_cndmask_b32_e64 v18, v18, v28, s[0:1]
	s_add_u32 s0, s14, s8
	s_addc_u32 s1, s15, s9
	s_add_u32 s8, s0, 0x3f80000
	s_addc_u32 s9, s1, 0
	s_ashr_i32 s7, s6, 31
	s_lshl_b64 s[0:1], s[20:21], 7
	s_lshl_b64 s[10:11], s[6:7], 2
	s_add_u32 s0, s14, s0
	s_addc_u32 s1, s15, s1
	s_lshl_b64 s[12:13], s[6:7], 7
	s_add_u32 s14, s14, 0x4000400
	v_lshlrev_b32_e32 v28, 2, v30
	v_lshlrev_b32_e32 v30, 2, v18
	v_lshl_add_u64 v[18:19], s[0:1], 0, v[16:17]
	s_addc_u32 s15, s15, 0
	s_lshl_b64 s[0:1], s[20:21], 11
	s_mov_b32 s19, 0x800000
	v_lshlrev_b32_e32 v25, 2, v22
	v_lshlrev_b32_e32 v26, 2, v23
	v_lshlrev_b32_e32 v27, 2, v29
	v_lshlrev_b32_e32 v29, 2, v31
	v_lshl_add_u64 v[18:19], v[18:19], 0, s[16:17]
	s_lshl_b64 s[16:17], s[6:7], 11
	v_lshl_add_u64 v[20:21], v[20:21], 3, s[0:1]
	s_movk_i32 s7, 0x7fff
	v_mov_b32_e32 v16, 1
	v_readlane_b32 s37, v250, 3
	v_readlane_b32 s38, v250, 4
	v_readlane_b32 s39, v250, 5
	v_readlane_b32 s40, v250, 6
	v_readlane_b32 s41, v250, 7
	v_readlane_b32 s44, v250, 10
	v_readlane_b32 s45, v250, 11
	v_readlane_b32 s46, v250, 12
	v_readlane_b32 s47, v250, 13
	v_readlane_b32 s48, v250, 14
	v_readlane_b32 s49, v250, 15
	v_readlane_b32 s50, v250, 16
	v_readlane_b32 s51, v250, 17
	s_waitcnt vmcnt(0)
	v_mov_b32_e32 v22, v1
	v_mov_b32_e32 v23, v3
	v_mov_b32_e32 v1, v2
	v_mov_b32_e32 v2, v5
	v_mov_b32_e32 v3, v7
	v_mov_b32_e32 v5, v6
	v_mov_b32_e32 v6, v9
	v_mov_b32_e32 v7, v11
	v_mov_b32_e32 v9, v10
	v_mov_b32_e32 v10, v13
	v_mov_b32_e32 v11, v15
	v_mov_b32_e32 v13, v14
	s_branch .LBB0_1544

; __device__ __forceinline__ void nr_pass(bf16* X, const bf16* Y, const float* SSQ, float* ssqX, const float* g, float* out  , int gw, int NGW, int lane) {
;     ...
;     for (int r = gw; r < M_REAL; r += NGW) {
;         const float part = SSQ[(size_t)r * 32 + (lane & 31)];
;         const float s = rsqrtf(half_sum32(part) * (1.0f / 1024.0f) + EPS);
;         v2u* x8 = (v2u*)(X + (size_t)r * 1024) + lane; const v2u* y8 = (const v2u*)(Y + (size_t)r * 1024) + lane;
;         f32x4 v[4]; float s2 = 0.f;
; #pragma unroll
;         for (int j = 0; j < 4; ++j) { const v2u xv = x8[64 * j], yv = __builtin_nontemporal_load(&y8[64 * j]);
;             v[j].x = bflo(xv.x) + bflo(yv.x) * s * gv[j].x; v[j].y = bfhi(xv.x) + bfhi(yv.x) * s * gv[j].y;
;             v[j].z = bflo(xv.y) + bflo(yv.y) * s * gv[j].z; v[j].w = bfhi(xv.y) + bfhi(yv.y) * s * gv[j].w;
;             s2 += (v[j].x * v[j].x + v[j].y * v[j].y) + (v[j].z * v[j].z + v[j].w * v[j].w); }
.LBB0_1544:
	global_load_dword v31, v[18:19], off
	v_lshl_add_u64 v[14:15], s[14:15], 0, v[20:21]
	v_lshl_add_u64 v[34:35], s[2:3], 0, v[20:21]
	s_waitcnt lgkmcnt(0)
	global_load_dwordx2 v[32:33], v[14:15], off offset:-1024
	global_load_dwordx2 v[36:37], v[34:35], off nt
	global_load_dwordx2 v[38:39], v[14:15], off offset:-512
	global_load_dwordx2 v[40:41], v[34:35], off offset:512 nt
	global_load_dwordx2 v[42:43], v[14:15], off
	global_load_dwordx2 v[44:45], v[34:35], off offset:1024 nt
	global_load_dwordx2 v[46:47], v[14:15], off offset:512
	global_load_dwordx2 v[48:49], v[34:35], off offset:1536 nt
	v_lshl_add_u64 v[254:255], v[14:15], 0, s[16:17]
	v_lshl_add_u64 v[254:255], v[254:255], 0, v[252:253]
	global_load_dword v251, v[254:255], off offset:-1024
	v_lshl_add_u64 v[254:255], v[34:35], 0, s[16:17]
	v_lshl_add_u64 v[254:255], v[254:255], 0, v[252:253]
	global_load_dword v251, v[254:255], off
	s_waitcnt vmcnt(8)
	v_lshlrev_b32_e32 v51, 16, v37
	v_lshlrev_b32_e32 v50, 16, v36
	ds_bpermute_b32 v56, v25, v31
	v_and_b32_e32 v37, 0xffff0000, v37
	v_and_b32_e32 v36, 0xffff0000, v36
	s_waitcnt vmcnt(6)
	v_lshlrev_b32_e32 v55, 16, v41
	v_lshlrev_b32_e32 v54, 16, v40
	s_waitcnt lgkmcnt(0)
	v_add_f32_e32 v31, v31, v56
	ds_bpermute_b32 v56, v26, v31
	v_and_b32_e32 v41, 0xffff0000, v41
	v_and_b32_e32 v40, 0xffff0000, v40
	v_lshlrev_b32_e32 v35, 16, v33
	v_lshlrev_b32_e32 v34, 16, v32
	s_waitcnt lgkmcnt(0)
	v_add_f32_e32 v31, v31, v56
	ds_bpermute_b32 v60, v27, v31
	v_and_b32_e32 v33, 0xffff0000, v33
	v_and_b32_e32 v32, 0xffff0000, v32
	v_lshlrev_b32_e32 v53, 16, v39
	v_lshlrev_b32_e32 v52, 16, v38
	s_waitcnt lgkmcnt(0)
	v_add_f32_e32 v31, v31, v60
	ds_bpermute_b32 v60, v28, v31
	v_and_b32_e32 v39, 0xffff0000, v39
	v_and_b32_e32 v38, 0xffff0000, v38
	s_waitcnt vmcnt(4)
	v_lshlrev_b32_e32 v59, 16, v45
	v_lshlrev_b32_e32 v58, 16, v44
	s_waitcnt lgkmcnt(0)
	v_add_f32_e32 v31, v31, v60
	ds_bpermute_b32 v64, v29, v31
	v_and_b32_e32 v45, 0xffff0000, v45
	v_and_b32_e32 v44, 0xffff0000, v44
	s_waitcnt vmcnt(2)
	v_lshlrev_b32_e32 v63, 16, v49
	v_lshlrev_b32_e32 v62, 16, v48
	s_waitcnt lgkmcnt(0)
	v_add_f32_e32 v31, v31, v64
	v_fmamk_f32 v31, v31, 0x3a800000, v24
	v_mul_f32_e32 v64, 0x4b800000, v31
	v_cmp_gt_f32_e64 s[0:1], s19, v31
	v_and_b32_e32 v49, 0xffff0000, v49
	v_and_b32_e32 v48, 0xffff0000, v48
	v_cndmask_b32_e64 v31, v31, v64, s[0:1]
	v_rsq_f32_e32 v31, v31
	v_lshlrev_b32_e32 v57, 16, v43
	v_lshlrev_b32_e32 v56, 16, v42
	v_and_b32_e32 v43, 0xffff0000, v43
	v_mul_f32_e32 v64, 0x45800000, v31
	v_cndmask_b32_e64 v64, v31, v64, s[0:1]
	v_pk_mul_f32 v[36:37], v[64:65], v[36:37] op_sel_hi:[0,1]
	v_pk_mul_f32 v[40:41], v[64:65], v[40:41] op_sel_hi:[0,1]
	v_and_b32_e32 v42, 0xffff0000, v42
	v_lshlrev_b32_e32 v61, 16, v47
	v_lshlrev_b32_e32 v60, 16, v46
	v_and_b32_e32 v47, 0xffff0000, v47
	v_and_b32_e32 v46, 0xffff0000, v46
	v_pk_mul_f32 v[50:51], v[64:65], v[50:51] op_sel_hi:[0,1]
	v_pk_mul_f32 v[54:55], v[64:65], v[54:55] op_sel_hi:[0,1]
	v_pk_mul_f32 v[58:59], v[64:65], v[58:59] op_sel_hi:[0,1]
	v_pk_mul_f32 v[44:45], v[64:65], v[44:45] op_sel_hi:[0,1]
	v_pk_mul_f32 v[48:49], v[64:65], v[48:49] op_sel_hi:[0,1]
	v_pk_fma_f32 v[32:33], v[10:11], v[36:37], v[32:33]
	v_pk_fma_f32 v[38:39], v[22:23], v[40:41], v[38:39]
	v_pk_fma_f32 v[34:35], v[12:13], v[50:51], v[34:35]
	v_pk_fma_f32 v[36:37], v[0:1], v[54:55], v[52:53]
	v_pk_fma_f32 v[40:41], v[4:5], v[58:59], v[56:57]
	v_pk_fma_f32 v[42:43], v[2:3], v[44:45], v[42:43]
	v_pk_fma_f32 v[46:47], v[6:7], v[48:49], v[46:47]
	v_pk_mul_f32 v[48:49], v[32:33], v[32:33]
	v_and_b32_sdwa v57, v33, v16 dst_sel:DWORD dst_unused:UNUSED_PAD src0_sel:WORD_1 src1_sel:DWORD
	v_and_b32_sdwa v58, v32, v16 dst_sel:DWORD dst_unused:UNUSED_PAD src0_sel:WORD_1 src1_sel:DWORD
	v_pk_mul_f32 v[50:51], v[38:39], v[38:39]
	v_pk_mul_f32 v[62:63], v[64:65], v[62:63] op_sel_hi:[0,1]
	v_and_b32_sdwa v31, v35, v16 dst_sel:DWORD dst_unused:UNUSED_PAD src0_sel:WORD_1 src1_sel:DWORD
	v_and_b32_sdwa v56, v34, v16 dst_sel:DWORD dst_unused:UNUSED_PAD src0_sel:WORD_1 src1_sel:DWORD
	v_pk_mul_f32 v[52:53], v[42:43], v[42:43]
	v_pk_fma_f32 v[48:49], v[34:35], v[34:35], v[48:49]
	v_add3_u32 v57, v33, v57, s7
	v_add3_u32 v58, v32, v58, s7
	v_pk_fma_f32 v[32:33], v[36:37], v[36:37], v[50:51]
	v_pk_fma_f32 v[44:45], v[8:9], v[62:63], v[60:61]
	v_and_b32_sdwa v59, v37, v16 dst_sel:DWORD dst_unused:UNUSED_PAD src0_sel:WORD_1 src1_sel:DWORD
	v_and_b32_sdwa v60, v36, v16 dst_sel:DWORD dst_unused:UNUSED_PAD src0_sel:WORD_1 src1_sel:DWORD
	v_pk_mul_f32 v[54:55], v[46:47], v[46:47]
	v_add3_u32 v56, v34, v56, s7
	v_add3_u32 v31, v35, v31, s7
	v_pk_fma_f32 v[34:35], v[40:41], v[40:41], v[52:53]
	v_add_f32_e32 v32, v32, v33
	v_add_f32_e32 v33, v48, v49
	v_add3_u32 v50, v36, v60, s7
	v_add3_u32 v51, v37, v59, s7
	v_pk_fma_f32 v[36:37], v[44:45], v[44:45], v[54:55]
	v_add_f32_e32 v34, v34, v35
	v_add_f32_e32 v32, v33, v32
	v_add_f32_e32 v35, v36, v37
	v_add_f32_e32 v32, v34, v32
	v_add_f32_e32 v32, v32, v35
	ds_bpermute_b32 v33, v25, v32
	v_and_b32_sdwa v61, v39, v16 dst_sel:DWORD dst_unused:UNUSED_PAD src0_sel:WORD_1 src1_sel:DWORD
	v_add3_u32 v39, v39, v61, s7
	v_and_b32_e32 v37, 0xffff0000, v39
	v_and_b32_e32 v35, 0xffff0000, v57
	s_waitcnt lgkmcnt(0)
; __device__ __forceinline__ unsigned pk2(float lo, float hi) { return f2bf(lo) | (f2bf(hi) << 16); }
; __device__ __forceinline__ void nr_pass(bf16* X, const bf16* Y, const float* SSQ, float* ssqX, const float* g, float* out  , int gw, int NGW, int lane) {
;     ...
;             s2 = wave_sum(s2);
; #pragma unroll
;             for (int j = 0; j < 4; ++j) x8[64 * j] = (v2u){pk2(v[j].x, v[j].y), pk2(v[j].z, v[j].w)};
;             if (lane == 0) ssqX[r] = s2;
	v_add_f32_e32 v32, v32, v33
	ds_bpermute_b32 v33, v26, v32
	v_and_b32_sdwa v62, v38, v16 dst_sel:DWORD dst_unused:UNUSED_PAD src0_sel:WORD_1 src1_sel:DWORD
	v_and_b32_sdwa v66, v42, v16 dst_sel:DWORD dst_unused:UNUSED_PAD src0_sel:WORD_1 src1_sel:DWORD
	v_add3_u32 v38, v38, v62, s7
	v_and_b32_sdwa v67, v45, v16 dst_sel:DWORD dst_unused:UNUSED_PAD src0_sel:WORD_1 src1_sel:DWORD
	s_waitcnt lgkmcnt(0)
	v_add_f32_e32 v32, v32, v33
	ds_bpermute_b32 v39, v27, v32
	v_or_b32_sdwa v33, v35, v31 dst_sel:DWORD dst_unused:UNUSED_PAD src0_sel:DWORD src1_sel:WORD_1
	v_and_b32_sdwa v68, v44, v16 dst_sel:DWORD dst_unused:UNUSED_PAD src0_sel:WORD_1 src1_sel:DWORD
	v_and_b32_sdwa v69, v47, v16 dst_sel:DWORD dst_unused:UNUSED_PAD src0_sel:WORD_1 src1_sel:DWORD
	v_add3_u32 v34, v42, v66, s7
	s_waitcnt lgkmcnt(0)
	v_add_f32_e32 v31, v32, v39
	ds_bpermute_b32 v39, v28, v31
	v_and_b32_e32 v38, 0xffff0000, v38
	v_add3_u32 v42, v44, v68, s7
	v_add3_u32 v44, v45, v67, s7
	v_add3_u32 v45, v47, v69, s7
	s_waitcnt lgkmcnt(0)
	v_add_f32_e32 v31, v31, v39
	v_and_b32_e32 v47, 0xffff0000, v34
	v_or_b32_sdwa v34, v38, v50 dst_sel:DWORD dst_unused:UNUSED_PAD src0_sel:DWORD src1_sel:WORD_1
	ds_bpermute_b32 v38, v29, v31
	v_and_b32_sdwa v65, v43, v16 dst_sel:DWORD dst_unused:UNUSED_PAD src0_sel:WORD_1 src1_sel:DWORD
	v_and_b32_sdwa v63, v41, v16 dst_sel:DWORD dst_unused:UNUSED_PAD src0_sel:WORD_1 src1_sel:DWORD
	v_and_b32_sdwa v64, v40, v16 dst_sel:DWORD dst_unused:UNUSED_PAD src0_sel:WORD_1 src1_sel:DWORD
	v_add3_u32 v43, v43, v65, s7
	v_and_b32_e32 v36, 0xffff0000, v58
	v_add3_u32 v40, v40, v64, s7
	v_add3_u32 v41, v41, v63, s7
	v_and_b32_e32 v43, 0xffff0000, v43
	v_or_b32_sdwa v32, v36, v56 dst_sel:DWORD dst_unused:UNUSED_PAD src0_sel:DWORD src1_sel:WORD_1
	s_waitcnt lgkmcnt(0)
	v_add_f32_e32 v31, v31, v38
	v_or_b32_sdwa v35, v37, v51 dst_sel:DWORD dst_unused:UNUSED_PAD src0_sel:DWORD src1_sel:WORD_1
	v_or_b32_sdwa v37, v43, v41 dst_sel:DWORD dst_unused:UNUSED_PAD src0_sel:DWORD src1_sel:WORD_1
	v_or_b32_sdwa v36, v47, v40 dst_sel:DWORD dst_unused:UNUSED_PAD src0_sel:DWORD src1_sel:WORD_1
	global_store_dwordx2 v[14:15], v[32:33], off offset:-1024
	global_store_dwordx2 v[14:15], v[34:35], off offset:-512
	global_store_dwordx2 v[14:15], v[36:37], off
	ds_bpermute_b32 v32, v30, v31
	v_and_b32_sdwa v70, v46, v16 dst_sel:DWORD dst_unused:UNUSED_PAD src0_sel:WORD_1 src1_sel:DWORD
	v_add3_u32 v46, v46, v70, s7
	v_and_b32_e32 v33, 0xffff0000, v45
	v_and_b32_e32 v34, 0xffff0000, v46
	v_or_b32_sdwa v35, v33, v44 dst_sel:DWORD dst_unused:UNUSED_PAD src0_sel:DWORD src1_sel:WORD_1
	v_or_b32_sdwa v34, v34, v42 dst_sel:DWORD dst_unused:UNUSED_PAD src0_sel:DWORD src1_sel:WORD_1
	global_store_dwordx2 v[14:15], v[34:35], off offset:512
	s_and_saveexec_b64 s[0:1], vcc
	s_cbranch_execz .LBB0_1543
	s_waitcnt lgkmcnt(0)
	v_add_f32_e32 v14, v31, v32
	global_store_dword v17, v14, s[8:9]
	s_branch .LBB0_1543

; __device__ __forceinline__ void nr_pass(bf16* X, const bf16* Y, const float* SSQ, float* ssqX, const float* g, float* out  , int gw, int NGW, int lane) {
;     f32x4 gv[4];
; #pragma unroll
;     for (int j = 0; j < 4; ++j) gv[j] = *((const f32x4*)g + lane + 64 * j);
;     for (int r = gw; r < M_REAL; r += NGW) {
;         const float part = SSQ[(size_t)r * 32 + (lane & 31)];
;         const float s = rsqrtf(half_sum32(part) * (1.0f / 1024.0f) + EPS);
.Lnr_go_p7l1:
	v_mbcnt_lo_u32_b32 v252, -1, 0
	v_mbcnt_hi_u32_b32 v252, -1, v252
	v_mul_u32_u24_e32 v252, 24, v252
	v_mov_b32_e32 v253, 0
	s_add_i32 s28, s1, s0
	s_cmp_ge_i32 s28, s63
	s_cbranch_scc1 .LBB0_1768
	v_ashrrev_i32_e32 v183, 31, v182
	v_lshlrev_b64 v[16:17], 4, v[182:183]
	v_lshl_add_u64 v[12:13], s[88:89], 0, v[16:17]
	s_mov_b64 s[6:7], 0x1000
	v_lshl_add_u64 v[14:15], v[12:13], 0, s[6:7]
	v_add_co_u32_e32 v12, vcc, 0x1000, v12
	global_load_dwordx4 v[0:3], v[14:15], off offset:1024
	s_waitcnt lgkmcnt(0)
	global_load_dwordx4 v[4:7], v[14:15], off offset:2048
	global_load_dwordx4 v[8:11], v[14:15], off offset:3072
	v_addc_co_u32_e32 v13, vcc, 0, v13, vcc
	global_load_dwordx4 v[12:15], v[12:13], off
	v_mbcnt_lo_u32_b32 v18, -1, 0
	v_mbcnt_hi_u32_b32 v18, -1, v18
	s_lshl_b32 s6, s2, 3
	v_and_b32_e32 v19, 64, v18
	s_cmp_lg_u64 s[90:91], 0
	v_xor_b32_e32 v21, 1, v18
	v_add_u32_e32 v19, 64, v19
	v_xor_b32_e32 v22, 2, v18
	s_cselect_b64 s[12:13], -1, 0
	s_add_i32 s30, s28, 0xffff7f00
	s_ashr_i32 s7, s0, 31
	s_ashr_i32 s8, s1, 31
	v_cmp_lt_i32_e32 vcc, v21, v19
	v_xor_b32_e32 v23, 4, v18
	s_add_u32 s0, s0, s1
	v_cndmask_b32_e32 v21, v18, v21, vcc
	v_cmp_lt_i32_e32 vcc, v22, v19
	v_xor_b32_e32 v24, 8, v18
	s_addc_u32 s1, s7, s8
	v_cndmask_b32_e32 v22, v18, v22, vcc
	v_cmp_lt_i32_e32 vcc, v23, v19
	v_xor_b32_e32 v25, 16, v18
	s_lshl_b64 s[14:15], s[0:1], 2
	v_cndmask_b32_e32 v23, v18, v23, vcc
	v_cmp_lt_i32_e32 vcc, v24, v19
	v_xor_b32_e32 v26, 32, v18
	s_add_u32 s31, s14, 0x3f80000
	v_cndmask_b32_e32 v24, v18, v24, vcc
	v_cmp_lt_i32_e32 vcc, v25, v19
	v_and_b32_e32 v20, 31, v182
	s_addc_u32 s33, s15, 0
	v_cndmask_b32_e32 v25, v18, v25, vcc
	v_cmp_lt_i32_e32 vcc, v26, v19
	s_lshl_b64 s[16:17], s[0:1], 11
	s_lshl_b64 s[0:1], s[0:1], 7
	s_mov_b64 s[20:21], 0x3700000
	v_cndmask_b32_e32 v18, v18, v26, vcc
	v_lshlrev_b32_e32 v41, 2, v21
	s_ashr_i32 s7, s6, 31
	v_lshl_or_b32 v20, v20, 2, s0
	v_mov_b32_e32 v21, s1
	s_mov_b32 s9, 0
	v_cmp_eq_u32_e64 s[2:3], 0, v182
	v_mov_b32_e32 v40, 0x358637bd
	s_mov_b32 s29, 0x800000
	s_mov_b64 s[10:11], 0x4000000
	v_lshl_add_u64 v[16:17], s[90:91], 0, v[16:17]
	v_lshlrev_b32_e32 v42, 2, v22
	v_lshlrev_b32_e32 v43, 2, v23
	v_lshlrev_b32_e32 v44, 2, v24
	v_lshlrev_b32_e32 v45, 2, v25
	v_lshlrev_b32_e32 v46, 2, v18
	s_lshl_b64 s[14:15], s[6:7], 2
	v_lshl_add_u64 v[18:19], v[182:183], 3, s[16:17]
	s_lshl_b64 s[16:17], s[6:7], 11
	s_lshl_b64 s[18:19], s[6:7], 7
	v_lshl_add_u64 v[20:21], v[20:21], 0, s[20:21]
	s_brev_b32 s7, 32
	s_mov_b32 s34, 0xc100000
	s_mov_b64 s[20:21], 0x4000200
	s_mov_b64 s[22:23], 0x4000400
	s_mov_b64 s[24:25], 0x4000600
	s_mov_b32 s35, 0xc000
	s_movk_i32 s36, 0x7fff
	v_mov_b32_e32 v47, 0
	v_mov_b32_e32 v48, 1
	s_waitcnt vmcnt(0)
	v_mov_b32_e32 v22, v1
	v_mov_b32_e32 v23, v3
	v_mov_b32_e32 v1, v2
	v_mov_b32_e32 v2, v5
	v_mov_b32_e32 v3, v7
	v_mov_b32_e32 v5, v6
	v_mov_b32_e32 v6, v9
	v_mov_b32_e32 v7, v11
	v_mov_b32_e32 v9, v10
	v_mov_b32_e32 v10, v13
	v_mov_b32_e32 v11, v15
	v_mov_b32_e32 v13, v14
	s_branch .LBB0_1757

; __device__ __forceinline__ unsigned pk2(float lo, float hi) { return f2bf(lo) | (f2bf(hi) << 16); }
; __device__ __forceinline__ void nr_pass(bf16* X, const bf16* Y, const float* SSQ, float* ssqX, const float* g, float* out  , int gw, int NGW, int lane) {
;     ...
;     for (int r = gw; r < M_REAL; r += NGW) {
;         const float part = SSQ[(size_t)r * 32 + (lane & 31)];
;         const float s = rsqrtf(half_sum32(part) * (1.0f / 1024.0f) + EPS);
;         v2u* x8 = (v2u*)(X + (size_t)r * 1024) + lane; const v2u* y8 = (const v2u*)(Y + (size_t)r * 1024) + lane;
;         f32x4 v[4]; float s2 = 0.f;
; #pragma unroll
;         for (int j = 0; j < 4; ++j) { const v2u xv = x8[64 * j], yv = __builtin_nontemporal_load(&y8[64 * j]);
;             v[j].x = bflo(xv.x) + bflo(yv.x) * s * gv[j].x; v[j].y = bfhi(xv.x) + bfhi(yv.x) * s * gv[j].y;
;             v[j].z = bflo(xv.y) + bflo(yv.y) * s * gv[j].z; v[j].w = bfhi(xv.y) + bfhi(yv.y) * s * gv[j].w;
;             s2 += (v[j].x * v[j].x + v[j].y * v[j].y) + (v[j].z * v[j].z + v[j].w * v[j].w); }
;         if (out == nullptr) {
;             s2 = wave_sum(s2);
; #pragma unroll
;             for (int j = 0; j < 4; ++j) x8[64 * j] = (v2u){pk2(v[j].x, v[j].y), pk2(v[j].z, v[j].w)};
;             if (lane == 0) ssqX[r] = s2;
;         } else {
;             int pos; size_t orow;
;             if (r < ROWS_P) { const int sq = r / L_P; pos = r - sq * L_P; orow = (size_t)sq * 2048 + (pos - 16); }
;             else { const int q = r - ROWS_P, sq = q / L_S; pos = q - sq * L_S; orow = (size_t)NSEQ_P * 2048 + (size_t)sq * 16384 + (pos - 16); }
;             if (pos >= 16) { f32x4* o = (f32x4*)(out + orow * 1024) + lane;
; #pragma unroll
;                 for (int j = 0; j < 4; ++j) o[64 * j] = v[j]; }
.LBB0_1757:
	s_waitcnt lgkmcnt(0)
	v_lshl_add_u64 v[14:15], s[92:93], 0, v[18:19]
	v_lshl_add_u64 v[24:25], s[92:93], 0, v[20:21]
	v_add_co_u32_e32 v26, vcc, s7, v14
	s_nop 1
	v_addc_co_u32_e32 v27, vcc, 0, v15, vcc
	global_load_dword v49, v[24:25], off
	global_load_dwordx2 v[28:29], v[26:27], off
	v_add_co_u32_e32 v24, vcc, s34, v14
	s_waitcnt vmcnt(1)
	ds_bpermute_b32 v58, v41, v49
	v_addc_co_u32_e32 v25, vcc, 0, v15, vcc
	global_load_dwordx2 v[30:31], v[24:25], off nt
	global_load_dwordx2 v[32:33], v[26:27], off offset:512
	global_load_dwordx2 v[34:35], v[24:25], off offset:512 nt
	global_load_dwordx2 v[36:37], v[26:27], off offset:1024
	global_load_dwordx2 v[38:39], v[24:25], off offset:1024 nt
	global_load_dwordx2 v[50:51], v[26:27], off offset:1536
	global_load_dwordx2 v[52:53], v[24:25], off offset:1536 nt
	v_lshl_add_u64 v[254:255], v[26:27], 0, s[16:17]
	v_lshl_add_u64 v[254:255], v[254:255], 0, v[252:253]
	global_load_dword v251, v[254:255], off
	v_lshl_add_u64 v[254:255], v[24:25], 0, s[16:17]
	v_lshl_add_u64 v[254:255], v[254:255], 0, v[252:253]
	global_load_dword v251, v[254:255], off
	s_waitcnt vmcnt(9)
	v_lshlrev_b32_e32 v25, 16, v29
	s_waitcnt lgkmcnt(0)
	v_add_f32_e32 v49, v49, v58
	ds_bpermute_b32 v58, v42, v49
	v_lshlrev_b32_e32 v24, 16, v28
	v_and_b32_e32 v29, 0xffff0000, v29
	v_and_b32_e32 v28, 0xffff0000, v28
	s_and_b64 vcc, exec, s[12:13]
	s_waitcnt lgkmcnt(0)
	v_add_f32_e32 v49, v49, v58
	ds_bpermute_b32 v62, v43, v49
	s_waitcnt lgkmcnt(0)
	v_add_f32_e32 v49, v49, v62
	ds_bpermute_b32 v64, v44, v49
	s_waitcnt lgkmcnt(0)
	v_add_f32_e32 v49, v49, v64
	ds_bpermute_b32 v66, v45, v49
	s_waitcnt lgkmcnt(0)
	v_add_f32_e32 v49, v49, v66
	v_fmamk_f32 v49, v49, 0x3a800000, v40
	v_mul_f32_e32 v66, 0x4b800000, v49
	v_cmp_gt_f32_e64 s[0:1], s29, v49
	s_waitcnt vmcnt(8)
	v_lshlrev_b32_e32 v27, 16, v31
	v_cndmask_b32_e64 v49, v49, v66, s[0:1]
	v_rsq_f32_e32 v49, v49
	v_lshlrev_b32_e32 v26, 16, v30
	v_and_b32_e32 v31, 0xffff0000, v31
	v_and_b32_e32 v30, 0xffff0000, v30
	v_mul_f32_e32 v66, 0x45800000, v49
	s_waitcnt vmcnt(6)
	v_lshlrev_b32_e32 v57, 16, v35
	v_lshlrev_b32_e32 v56, 16, v34
	v_and_b32_e32 v35, 0xffff0000, v35
	v_and_b32_e32 v34, 0xffff0000, v34
	s_waitcnt vmcnt(5)
	v_lshlrev_b32_e32 v59, 16, v37
	v_lshlrev_b32_e32 v58, 16, v36
	s_waitcnt vmcnt(4)
	v_lshlrev_b32_e32 v61, 16, v39
	v_lshlrev_b32_e32 v60, 16, v38
	v_and_b32_e32 v63, 0xffff0000, v37
	v_and_b32_e32 v62, 0xffff0000, v36
	v_and_b32_e32 v37, 0xffff0000, v39
	v_and_b32_e32 v36, 0xffff0000, v38
	s_waitcnt vmcnt(2)
	v_lshlrev_b32_e32 v39, 16, v53
	v_lshlrev_b32_e32 v38, 16, v52
	v_and_b32_e32 v53, 0xffff0000, v53
	v_and_b32_e32 v52, 0xffff0000, v52
	v_cndmask_b32_e64 v66, v49, v66, s[0:1]
	v_lshlrev_b32_e32 v55, 16, v33
	v_lshlrev_b32_e32 v54, 16, v32
	v_and_b32_e32 v33, 0xffff0000, v33
	v_and_b32_e32 v32, 0xffff0000, v32
	v_lshlrev_b32_e32 v65, 16, v51
	v_lshlrev_b32_e32 v64, 16, v50
	v_and_b32_e32 v51, 0xffff0000, v51
	v_and_b32_e32 v50, 0xffff0000, v50
	v_pk_mul_f32 v[26:27], v[66:67], v[26:27] op_sel_hi:[0,1]
	v_pk_mul_f32 v[30:31], v[66:67], v[30:31] op_sel_hi:[0,1]
	v_pk_mul_f32 v[56:57], v[66:67], v[56:57] op_sel_hi:[0,1]
	v_pk_mul_f32 v[68:69], v[66:67], v[34:35] op_sel_hi:[0,1]
	v_pk_mul_f32 v[60:61], v[66:67], v[60:61] op_sel_hi:[0,1]
	v_pk_mul_f32 v[70:71], v[66:67], v[36:37] op_sel_hi:[0,1]
	v_pk_mul_f32 v[72:73], v[66:67], v[38:39] op_sel_hi:[0,1]
	v_pk_mul_f32 v[52:53], v[66:67], v[52:53] op_sel_hi:[0,1]
	v_pk_fma_f32 v[38:39], v[12:13], v[26:27], v[24:25]
	v_pk_fma_f32 v[36:37], v[10:11], v[30:31], v[28:29]
	v_pk_fma_f32 v[34:35], v[0:1], v[56:57], v[54:55]
	v_pk_fma_f32 v[32:33], v[22:23], v[68:69], v[32:33]
	v_pk_fma_f32 v[30:31], v[4:5], v[60:61], v[58:59]
	v_pk_fma_f32 v[28:29], v[2:3], v[70:71], v[62:63]
	v_pk_fma_f32 v[26:27], v[8:9], v[72:73], v[64:65]
	v_pk_fma_f32 v[24:25], v[6:7], v[52:53], v[50:51]
	s_cbranch_vccz .LBB0_1763
	s_add_i32 s38, s30, 0x8100
	s_cmp_gt_i32 s38, 0x80ff
	s_mov_b64 s[26:27], -1
	s_cbranch_scc1 .LBB0_1766
	s_andn2_b64 vcc, exec, s[26:27]
	s_cbranch_vccz .LBB0_1767
